# grid syncs 2..8 replaced by XCD-hierarchical barrier (one L2 writeback per XCD, atomic polling)
# speedup vs baseline: 1.1006x; 1.0615x over previous
; #define RUN_PHASE(k, fn)                                  \
;   if (ph_lo <= k && k <= ph_hi) {                         \
;     if (k == PROBE_DUP) { fn(p, smem); cg::this_grid().sync(); } \
;     fn(p, smem);                                          \
;     if (k < ph_hi) cg::this_grid().sync();                \
;   }
; __global__ void __launch_bounds__(512) mega(Params p, int ph_lo, int ph_hi) {
;     ...
;   RUN_PHASE(0, phase0)
;   RUN_PHASE(1, phase1)
.LBB0_218:
	s_or_b64 exec, exec, s[4:5]
	s_barrier
	v_cmp_eq_u32_e32 vcc, 0, v0
	s_and_saveexec_b64 s[4:5], vcc
	s_cbranch_execz .Lgb_post_done
	s_getreg_b32 s100, hwreg(HW_REG_XCC_ID, 0, 4)
	s_add_u32 s8, s88, 0xb20000
	s_addc_u32 s9, s89, 0
	s_and_b32 s100, s100, 7
	s_lshl_b32 s0, s100, 8
	v_mov_b32_e32 v1, s0
	v_mov_b32_e32 v2, 1
	global_atomic_add v1, v2, s[8:9]
	s_mov_b32 s98, 1
	s_mov_b32 s99, 1
.Lgb_post_done:
	s_or_b64 exec, exec, s[4:5]
.LBB0_219:
	s_cmp_gt_i32 s90, 1
	s_cselect_b64 s[0:1], -1, 0
	s_cmp_lt_i32 s91, 1
	s_cselect_b64 s[4:5], -1, 0
	s_or_b64 s[0:1], s[0:1], s[4:5]
	s_and_b64 vcc, exec, s[0:1]
	v_writelane_b32 v239, s92, 32
	s_nop 1
	v_writelane_b32 v239, s93, 33
	s_cbranch_vccnz .LBB0_524
	s_load_dword s81, s[92:93], 0xc0
	s_add_u32 s2, s92, 0xc0
	s_addc_u32 s3, s93, 0
	s_waitcnt lgkmcnt(0)
	s_and_b32 s0, s81, 7
	s_cmp_lg_u32 s0, 0
	s_cbranch_scc0 .LBB0_222
	s_movk_i32 s26, 0xbae
	s_mov_b32 s33, s94
	s_branch .LBB0_223

.LBB0_512:
	s_cmp_lt_i32 s91, 2
	s_cbranch_scc1 .LBB0_524
	s_waitcnt vmcnt(0) lgkmcnt(0)
	s_barrier
	v_cmp_eq_u32_e32 vcc, 0, v0
	s_and_saveexec_b64 s[4:5], vcc
	s_cbranch_execz .Lgb0_done
	s_add_u32 s8, s88, 0xb20000
	s_addc_u32 s9, s89, 0
	v_mov_b32_e32 v10, 0
	v_mov_b32_e32 v11, 1
	s_load_dword s10, s[92:93], 0xc0
	s_movk_i32 s11, 0x800
.Lgb0_census:
	global_atomic_add v1, v10, v10, s[8:9] offset:0 sc0
	global_atomic_add v2, v10, v10, s[8:9] offset:256 sc0
	global_atomic_add v3, v10, v10, s[8:9] offset:512 sc0
	global_atomic_add v4, v10, v10, s[8:9] offset:768 sc0
	global_atomic_add v5, v10, v10, s[8:9] offset:1024 sc0
	global_atomic_add v6, v10, v10, s[8:9] offset:1280 sc0
	global_atomic_add v7, v10, v10, s[8:9] offset:1536 sc0
	global_atomic_add v8, v10, v10, s[8:9] offset:1792 sc0
	s_waitcnt vmcnt(0) lgkmcnt(0)
	v_readfirstlane_b32 s12, v1
	v_readfirstlane_b32 s13, v2
	v_readfirstlane_b32 s14, v3
	v_readfirstlane_b32 s15, v4
	v_readfirstlane_b32 s16, v5
	v_readfirstlane_b32 s17, v6
	v_readfirstlane_b32 s18, v7
	v_readfirstlane_b32 s19, v8
	s_mov_b32 s20, 0
	s_mov_b32 s21, 0
	s_add_i32 s20, s20, s12
	s_cmp_lg_u32 s12, 0
	s_addc_u32 s21, s21, 0
	s_add_i32 s20, s20, s13
	s_cmp_lg_u32 s13, 0
	s_addc_u32 s21, s21, 0
	s_add_i32 s20, s20, s14
	s_cmp_lg_u32 s14, 0
	s_addc_u32 s21, s21, 0
	s_add_i32 s20, s20, s15
	s_cmp_lg_u32 s15, 0
	s_addc_u32 s21, s21, 0
	s_add_i32 s20, s20, s16
	s_cmp_lg_u32 s16, 0
	s_addc_u32 s21, s21, 0
	s_add_i32 s20, s20, s17
	s_cmp_lg_u32 s17, 0
	s_addc_u32 s21, s21, 0
	s_add_i32 s20, s20, s18
	s_cmp_lg_u32 s18, 0
	s_addc_u32 s21, s21, 0
	s_add_i32 s20, s20, s19
	s_cmp_lg_u32 s19, 0
	s_addc_u32 s21, s21, 0
	s_cmp_eq_u32 s20, s10
	s_cbranch_scc1 .Lgb0_census_ok
	s_sleep 2
	s_sub_i32 s11, s11, 1
	s_cmp_lg_u32 s11, 0
	s_cbranch_scc1 .Lgb0_census
.Lgb0_census_ok:
	s_mov_b32 s98, s12
	s_cmp_eq_u32 s100, 1
	s_cselect_b32 s98, s13, s98
	s_cmp_eq_u32 s100, 2
	s_cselect_b32 s98, s14, s98
	s_cmp_eq_u32 s100, 3
	s_cselect_b32 s98, s15, s98
	s_cmp_eq_u32 s100, 4
	s_cselect_b32 s98, s16, s98
	s_cmp_eq_u32 s100, 5
	s_cselect_b32 s98, s17, s98
	s_cmp_eq_u32 s100, 6
	s_cselect_b32 s98, s18, s98
	s_cmp_eq_u32 s100, 7
	s_cselect_b32 s98, s19, s98
	s_max_u32 s98, s98, 1
	s_max_u32 s99, s21, 1
	s_lshl_b32 s0, s100, 8
	s_add_i32 s1, s0, 0x1000
	v_mov_b32_e32 v1, s1
	global_atomic_add v2, v1, v11, s[8:9] sc0
	s_add_i32 s2, s0, 0x2000
	s_mul_i32 s3, s98, 1
	s_mul_i32 s6, s99, 1
	s_waitcnt vmcnt(0)
	v_readfirstlane_b32 s7, v2
	s_add_i32 s7, s7, 1
	s_cmp_eq_u32 s7, s3
	s_cbranch_scc0 .Lgb0_wait
	buffer_wbl2 sc1
	s_waitcnt vmcnt(0)
	v_mov_b32_e32 v1, 0x3000
	global_atomic_add v2, v1, v11, s[8:9] sc0
	s_waitcnt vmcnt(0)
	v_readfirstlane_b32 s7, v2
	s_add_i32 s7, s7, 1
	v_mov_b32_e32 v1, 0x3100
	s_cmp_eq_u32 s7, s6
	s_cbranch_scc0 .Lgb0_topspin_init
	global_atomic_add v1, v11, s[8:9]
	s_branch .Lgb0_release
.Lgb0_topspin_init:
	s_movk_i32 s11, 0x800
.Lgb0_topspin:
	global_atomic_add v2, v1, v10, s[8:9] sc0
	s_waitcnt vmcnt(0)
	v_readfirstlane_b32 s7, v2
	s_cmp_gt_u32 s7, 0
	s_cbranch_scc1 .Lgb0_release
	s_sleep 1
	s_sub_i32 s11, s11, 1
	s_cmp_lg_u32 s11, 0
	s_cbranch_scc1 .Lgb0_topspin
.Lgb0_release:
	buffer_inv sc1
	v_mov_b32_e32 v1, s2
	global_atomic_add v1, v11, s[8:9]
	s_waitcnt vmcnt(0)
	s_branch .Lgb0_done
.Lgb0_wait:
	v_mov_b32_e32 v1, s2
	s_movk_i32 s11, 0x800
.Lgb0_spin:
	s_sleep 1
	global_atomic_add v2, v1, v10, s[8:9] sc0
	s_waitcnt vmcnt(0)
	v_readfirstlane_b32 s7, v2
	s_cmp_gt_u32 s7, 0
	s_cbranch_scc1 .Lgb0_acq
	s_sub_i32 s11, s11, 1
	s_cmp_lg_u32 s11, 0
	s_cbranch_scc1 .Lgb0_spin
.Lgb0_acq:
	buffer_inv sc1
	s_waitcnt vmcnt(0)

.LBB0_596:
	s_cmp_lt_i32 s91, 3
	s_cbranch_scc1 .LBB0_608
	s_waitcnt vmcnt(0) lgkmcnt(0)
	s_barrier
	v_cmp_eq_u32_e32 vcc, 0, v0
	s_and_saveexec_b64 s[4:5], vcc
	s_cbranch_execz .Lgb1_done
	s_add_u32 s8, s88, 0xb20000
	s_addc_u32 s9, s89, 0
	v_mov_b32_e32 v10, 0
	v_mov_b32_e32 v11, 1
	s_lshl_b32 s0, s100, 8
	s_add_i32 s1, s0, 0x1000
	v_mov_b32_e32 v1, s1
	global_atomic_add v2, v1, v11, s[8:9] sc0
	s_add_i32 s2, s0, 0x2000
	s_mul_i32 s3, s98, 2
	s_mul_i32 s6, s99, 2
	s_waitcnt vmcnt(0)
	v_readfirstlane_b32 s7, v2
	s_add_i32 s7, s7, 1
	s_cmp_eq_u32 s7, s3
	s_cbranch_scc0 .Lgb1_wait
	buffer_wbl2 sc1
	s_waitcnt vmcnt(0)
	v_mov_b32_e32 v1, 0x3000
	global_atomic_add v2, v1, v11, s[8:9] sc0
	s_waitcnt vmcnt(0)
	v_readfirstlane_b32 s7, v2
	s_add_i32 s7, s7, 1
	v_mov_b32_e32 v1, 0x3100
	s_cmp_eq_u32 s7, s6
	s_cbranch_scc0 .Lgb1_topspin_init
	global_atomic_add v1, v11, s[8:9]
	s_branch .Lgb1_release

.Lgb1_topspin:
	global_atomic_add v2, v1, v10, s[8:9] sc0
	s_waitcnt vmcnt(0)
	v_readfirstlane_b32 s7, v2
	s_cmp_gt_u32 s7, 1
	s_cbranch_scc1 .Lgb1_release
	s_sleep 1
	s_sub_i32 s11, s11, 1
	s_cmp_lg_u32 s11, 0
	s_cbranch_scc1 .Lgb1_topspin

.Lgb1_spin:
	s_sleep 1
	global_atomic_add v2, v1, v10, s[8:9] sc0
	s_waitcnt vmcnt(0)
	v_readfirstlane_b32 s7, v2
	s_cmp_gt_u32 s7, 1
	s_cbranch_scc1 .Lgb1_acq
	s_sub_i32 s11, s11, 1
	s_cmp_lg_u32 s11, 0
	s_cbranch_scc1 .Lgb1_spin

.LBB0_664:
	s_cmp_lt_i32 s91, 4
	s_cbranch_scc1 .LBB0_676
	s_waitcnt vmcnt(0) lgkmcnt(0)
	s_barrier
	v_cmp_eq_u32_e32 vcc, 0, v0
	s_and_saveexec_b64 s[4:5], vcc
	s_cbranch_execz .Lgb2_done
	s_add_u32 s8, s88, 0xb20000
	s_addc_u32 s9, s89, 0
	v_mov_b32_e32 v10, 0
	v_mov_b32_e32 v11, 1
	s_lshl_b32 s0, s100, 8
	s_add_i32 s1, s0, 0x1000
	v_mov_b32_e32 v1, s1
	global_atomic_add v2, v1, v11, s[8:9] sc0
	s_add_i32 s2, s0, 0x2000
	s_mul_i32 s3, s98, 3
	s_mul_i32 s6, s99, 3
	s_waitcnt vmcnt(0)
	v_readfirstlane_b32 s7, v2
	s_add_i32 s7, s7, 1
	s_cmp_eq_u32 s7, s3
	s_cbranch_scc0 .Lgb2_wait
	buffer_wbl2 sc1
	s_waitcnt vmcnt(0)
	v_mov_b32_e32 v1, 0x3000
	global_atomic_add v2, v1, v11, s[8:9] sc0
	s_waitcnt vmcnt(0)
	v_readfirstlane_b32 s7, v2
	s_add_i32 s7, s7, 1
	v_mov_b32_e32 v1, 0x3100
	s_cmp_eq_u32 s7, s6
	s_cbranch_scc0 .Lgb2_topspin_init
	global_atomic_add v1, v11, s[8:9]
	s_branch .Lgb2_release

.Lgb2_topspin:
	global_atomic_add v2, v1, v10, s[8:9] sc0
	s_waitcnt vmcnt(0)
	v_readfirstlane_b32 s7, v2
	s_cmp_gt_u32 s7, 2
	s_cbranch_scc1 .Lgb2_release
	s_sleep 1
	s_sub_i32 s11, s11, 1
	s_cmp_lg_u32 s11, 0
	s_cbranch_scc1 .Lgb2_topspin

.Lgb2_spin:
	s_sleep 1
	global_atomic_add v2, v1, v10, s[8:9] sc0
	s_waitcnt vmcnt(0)
	v_readfirstlane_b32 s7, v2
	s_cmp_gt_u32 s7, 2
	s_cbranch_scc1 .Lgb2_acq
	s_sub_i32 s11, s11, 1
	s_cmp_lg_u32 s11, 0
	s_cbranch_scc1 .Lgb2_spin

.LBB0_718:
	s_cmp_lt_i32 s91, 5
	s_cbranch_scc1 .LBB0_730
	s_waitcnt vmcnt(0) lgkmcnt(0)
	s_barrier
	v_cmp_eq_u32_e32 vcc, 0, v0
	s_and_saveexec_b64 s[4:5], vcc
	s_cbranch_execz .Lgb3_done
	s_add_u32 s8, s88, 0xb20000
	s_addc_u32 s9, s89, 0
	v_mov_b32_e32 v10, 0
	v_mov_b32_e32 v11, 1
	s_lshl_b32 s0, s100, 8
	s_add_i32 s1, s0, 0x1000
	v_mov_b32_e32 v1, s1
	global_atomic_add v2, v1, v11, s[8:9] sc0
	s_add_i32 s2, s0, 0x2000
	s_mul_i32 s3, s98, 4
	s_mul_i32 s6, s99, 4
	s_waitcnt vmcnt(0)
	v_readfirstlane_b32 s7, v2
	s_add_i32 s7, s7, 1
	s_cmp_eq_u32 s7, s3
	s_cbranch_scc0 .Lgb3_wait
	buffer_wbl2 sc1
	s_waitcnt vmcnt(0)
	v_mov_b32_e32 v1, 0x3000
	global_atomic_add v2, v1, v11, s[8:9] sc0
	s_waitcnt vmcnt(0)
	v_readfirstlane_b32 s7, v2
	s_add_i32 s7, s7, 1
	v_mov_b32_e32 v1, 0x3100
	s_cmp_eq_u32 s7, s6
	s_cbranch_scc0 .Lgb3_topspin_init
	global_atomic_add v1, v11, s[8:9]
	s_branch .Lgb3_release

.Lgb3_topspin:
	global_atomic_add v2, v1, v10, s[8:9] sc0
	s_waitcnt vmcnt(0)
	v_readfirstlane_b32 s7, v2
	s_cmp_gt_u32 s7, 3
	s_cbranch_scc1 .Lgb3_release
	s_sleep 1
	s_sub_i32 s11, s11, 1
	s_cmp_lg_u32 s11, 0
	s_cbranch_scc1 .Lgb3_topspin

.Lgb3_spin:
	s_sleep 1
	global_atomic_add v2, v1, v10, s[8:9] sc0
	s_waitcnt vmcnt(0)
	v_readfirstlane_b32 s7, v2
	s_cmp_gt_u32 s7, 3
	s_cbranch_scc1 .Lgb3_acq
	s_sub_i32 s11, s11, 1
	s_cmp_lg_u32 s11, 0
	s_cbranch_scc1 .Lgb3_spin

; __device__ __forceinline__ void tile_range(int N, int& lo, int& hi, int& step) {
;   if ((gridDim.x & 7) == 0) {
;     const int x = blockIdx.x & 7, l = blockIdx.x >> 3;
;     lo = (int)((long long)x * N / 8) + l; hi = (int)((long long)(x + 1) * N / 8); step = gridDim.x >> 3;
;   } else { lo = blockIdx.x; hi = N; step = gridDim.x; }
; }
.Lgb3_done:
	s_or_b64 exec, exec, s[4:5]
	s_barrier
.LBB0_730:
	s_cmp_gt_i32 s90, 5
	s_cselect_b64 s[0:1], -1, 0
	s_cmp_lt_i32 s91, 5
	s_cselect_b64 s[4:5], -1, 0
	s_or_b64 s[0:1], s[0:1], s[4:5]
	s_and_b64 vcc, exec, s[0:1]
	s_cbranch_vccnz .LBB0_782
	s_load_dword s0, s[92:93], 0xc0
	s_add_u32 s6, s92, 0xc0
	s_addc_u32 s7, s93, 0
	s_waitcnt lgkmcnt(0)
	s_and_b32 s1, s0, 7
	s_cmp_lg_u32 s1, 0
	s_cbranch_scc0 .LBB0_733
	s_movk_i32 s3, 0x208
	s_mov_b32 s1, s94
	s_branch .LBB0_734

.LBB0_770:
	s_cmp_lt_i32 s91, 6
	s_cbranch_scc1 .LBB0_782
	s_waitcnt vmcnt(0) lgkmcnt(0)
	s_barrier
	v_cmp_eq_u32_e32 vcc, 0, v0
	s_and_saveexec_b64 s[4:5], vcc
	s_cbranch_execz .Lgb4_done
	s_add_u32 s8, s88, 0xb20000
	s_addc_u32 s9, s89, 0
	v_mov_b32_e32 v10, 0
	v_mov_b32_e32 v11, 1
	s_lshl_b32 s0, s100, 8
	s_add_i32 s1, s0, 0x1000
	v_mov_b32_e32 v1, s1
	global_atomic_add v2, v1, v11, s[8:9] sc0
	s_add_i32 s2, s0, 0x2000
	s_mul_i32 s3, s98, 5
	s_mul_i32 s6, s99, 5
	s_waitcnt vmcnt(0)
	v_readfirstlane_b32 s7, v2
	s_add_i32 s7, s7, 1
	s_cmp_eq_u32 s7, s3
	s_cbranch_scc0 .Lgb4_wait
	buffer_wbl2 sc1
	s_waitcnt vmcnt(0)
	v_mov_b32_e32 v1, 0x3000
	global_atomic_add v2, v1, v11, s[8:9] sc0
	s_waitcnt vmcnt(0)
	v_readfirstlane_b32 s7, v2
	s_add_i32 s7, s7, 1
	v_mov_b32_e32 v1, 0x3100
	s_cmp_eq_u32 s7, s6
	s_cbranch_scc0 .Lgb4_topspin_init
	global_atomic_add v1, v11, s[8:9]
	s_branch .Lgb4_release

.Lgb4_topspin:
	global_atomic_add v2, v1, v10, s[8:9] sc0
	s_waitcnt vmcnt(0)
	v_readfirstlane_b32 s7, v2
	s_cmp_gt_u32 s7, 4
	s_cbranch_scc1 .Lgb4_release
	s_sleep 1
	s_sub_i32 s11, s11, 1
	s_cmp_lg_u32 s11, 0
	s_cbranch_scc1 .Lgb4_topspin

.Lgb4_spin:
	s_sleep 1
	global_atomic_add v2, v1, v10, s[8:9] sc0
	s_waitcnt vmcnt(0)
	v_readfirstlane_b32 s7, v2
	s_cmp_gt_u32 s7, 4
	s_cbranch_scc1 .Lgb4_acq
	s_sub_i32 s11, s11, 1
	s_cmp_lg_u32 s11, 0
	s_cbranch_scc1 .Lgb4_spin

.LBB0_805:
	s_cmp_lt_i32 s91, 7
	s_cbranch_scc1 .LBB0_817
	s_waitcnt vmcnt(0) lgkmcnt(0)
	s_barrier
	v_cmp_eq_u32_e32 vcc, 0, v0
	s_and_saveexec_b64 s[4:5], vcc
	s_cbranch_execz .Lgb5_done
	s_add_u32 s8, s88, 0xb20000
	s_addc_u32 s9, s89, 0
	v_mov_b32_e32 v10, 0
	v_mov_b32_e32 v11, 1
	s_lshl_b32 s0, s100, 8
	s_add_i32 s1, s0, 0x1000
	v_mov_b32_e32 v1, s1
	global_atomic_add v2, v1, v11, s[8:9] sc0
	s_add_i32 s2, s0, 0x2000
	s_mul_i32 s3, s98, 6
	s_mul_i32 s6, s99, 6
	s_waitcnt vmcnt(0)
	v_readfirstlane_b32 s7, v2
	s_add_i32 s7, s7, 1
	s_cmp_eq_u32 s7, s3
	s_cbranch_scc0 .Lgb5_wait
	buffer_wbl2 sc1
	s_waitcnt vmcnt(0)
	v_mov_b32_e32 v1, 0x3000
	global_atomic_add v2, v1, v11, s[8:9] sc0
	s_waitcnt vmcnt(0)
	v_readfirstlane_b32 s7, v2
	s_add_i32 s7, s7, 1
	v_mov_b32_e32 v1, 0x3100
	s_cmp_eq_u32 s7, s6
	s_cbranch_scc0 .Lgb5_topspin_init
	global_atomic_add v1, v11, s[8:9]
	s_branch .Lgb5_release

.Lgb5_topspin:
	global_atomic_add v2, v1, v10, s[8:9] sc0
	s_waitcnt vmcnt(0)
	v_readfirstlane_b32 s7, v2
	s_cmp_gt_u32 s7, 5
	s_cbranch_scc1 .Lgb5_release
	s_sleep 1
	s_sub_i32 s11, s11, 1
	s_cmp_lg_u32 s11, 0
	s_cbranch_scc1 .Lgb5_topspin

.Lgb5_spin:
	s_sleep 1
	global_atomic_add v2, v1, v10, s[8:9] sc0
	s_waitcnt vmcnt(0)
	v_readfirstlane_b32 s7, v2
	s_cmp_gt_u32 s7, 5
	s_cbranch_scc1 .Lgb5_acq
	s_sub_i32 s11, s11, 1
	s_cmp_lg_u32 s11, 0
	s_cbranch_scc1 .Lgb5_spin

.LBB0_836:
	s_cmp_lt_i32 s91, 8
	s_cbranch_scc1 .LBB0_848
	s_waitcnt vmcnt(0) lgkmcnt(0)
	s_barrier
	v_cmp_eq_u32_e32 vcc, 0, v0
	s_and_saveexec_b64 s[4:5], vcc
	s_cbranch_execz .Lgb6_done
	s_add_u32 s8, s88, 0xb20000
	s_addc_u32 s9, s89, 0
	v_mov_b32_e32 v10, 0
	v_mov_b32_e32 v11, 1
	s_lshl_b32 s0, s100, 8
	s_add_i32 s1, s0, 0x1000
	v_mov_b32_e32 v1, s1
	global_atomic_add v2, v1, v11, s[8:9] sc0
	s_add_i32 s2, s0, 0x2000
	s_mul_i32 s3, s98, 7
	s_mul_i32 s6, s99, 7
	s_waitcnt vmcnt(0)
	v_readfirstlane_b32 s7, v2
	s_add_i32 s7, s7, 1
	s_cmp_eq_u32 s7, s3
	s_cbranch_scc0 .Lgb6_wait
	buffer_wbl2 sc1
	s_waitcnt vmcnt(0)
	v_mov_b32_e32 v1, 0x3000
	global_atomic_add v2, v1, v11, s[8:9] sc0
	s_waitcnt vmcnt(0)
	v_readfirstlane_b32 s7, v2
	s_add_i32 s7, s7, 1
	v_mov_b32_e32 v1, 0x3100
	s_cmp_eq_u32 s7, s6
	s_cbranch_scc0 .Lgb6_topspin_init
	global_atomic_add v1, v11, s[8:9]
	s_branch .Lgb6_release

.Lgb6_topspin:
	global_atomic_add v2, v1, v10, s[8:9] sc0
	s_waitcnt vmcnt(0)
	v_readfirstlane_b32 s7, v2
	s_cmp_gt_u32 s7, 6
	s_cbranch_scc1 .Lgb6_release
	s_sleep 1
	s_sub_i32 s11, s11, 1
	s_cmp_lg_u32 s11, 0
	s_cbranch_scc1 .Lgb6_topspin

.Lgb6_spin:
	s_sleep 1
	global_atomic_add v2, v1, v10, s[8:9] sc0
	s_waitcnt vmcnt(0)
	v_readfirstlane_b32 s7, v2
	s_cmp_gt_u32 s7, 6
	s_cbranch_scc1 .Lgb6_acq
	s_sub_i32 s11, s11, 1
	s_cmp_lg_u32 s11, 0
	s_cbranch_scc1 .Lgb6_spin

; __device__ void phase8(const Params& p, unsigned char* smem) {
;   unsigned char* ws = p.ws;
;   const float* part = (const float*)(ws + OFF_PART);
;   const int gtid = blockIdx.x * blockDim.x + threadIdx.x, gsz = gridDim.x * blockDim.x;
;   for (int i = gtid; i < 16 * 256 * 32; i += gsz) {
;     const int f4 = i & 31, tl = (i >> 5) & 255, tile = i >> 13;
;     const int ft = tile & 7, tt = 128 + (tile >> 3);
;     float* yp = p.out + O_Y + (size_t)(tt * 256 + tl) * 1024 + ft * 128 + f4 * 4;
;     float4 y = *(const float4*)yp;
.Lgb6_done:
	s_or_b64 exec, exec, s[4:5]
	s_barrier
.LBB0_848:
	s_cmp_gt_i32 s90, 8
	s_cselect_b64 s[0:1], -1, 0
	s_cmp_lt_i32 s91, 8
	s_cselect_b64 s[4:5], -1, 0
	s_or_b64 s[0:1], s[0:1], s[4:5]
	s_and_b64 vcc, exec, s[0:1]
	s_cbranch_vccnz .LBB0_864
	s_load_dword s6, s[92:93], 0xc0
	s_add_u32 s0, s92, 0xc0
	s_addc_u32 s1, s93, 0
	v_mov_b32_e32 v3, 0
	v_and_b32_e32 v1, 0x3ff, v0
	s_waitcnt lgkmcnt(0)
	s_cmp_lt_u32 s94, s6
	s_cselect_b32 s3, 12, 18
	s_add_u32 s4, s0, s3
	s_addc_u32 s5, s1, 0
	global_load_ushort v2, v3, s[4:5]
	s_mov_b32 s2, 0x20000
	s_waitcnt vmcnt(0)
	v_mul_lo_u32 v4, s94, v2
	v_add_u32_e32 v4, v4, v1
	v_cmp_gt_i32_e32 vcc, s2, v4
	s_and_saveexec_b64 s[2:3], vcc
	s_cbranch_execz .LBB0_852
	s_add_u32 s4, s88, 0x2020800
	v_mul_lo_u32 v5, s6, v2
	s_addc_u32 s5, s89, 0
	v_lshlrev_b32_e32 v6, 2, v4
	v_lshlrev_b32_e32 v7, 2, v5
	s_mov_b64 s[6:7], 0
	s_movk_i32 s8, 0xff00
	s_mov_b32 s9, 0x1ffff

; __global__ void __launch_bounds__(512) mega(Params p, int ph_lo, int ph_hi) {
;   __shared__ __align__(16) unsigned char smem[SMEM_BYTES];
	.amdhsa_kernel _Z4mega6Paramsii
		.amdhsa_group_segment_fixed_size 139264
		.amdhsa_private_segment_fixed_size 0
		.amdhsa_kernarg_size 448
		.amdhsa_user_sgpr_count 2
		.amdhsa_user_sgpr_dispatch_ptr 0
		.amdhsa_user_sgpr_queue_ptr 0
		.amdhsa_user_sgpr_kernarg_segment_ptr 1
		.amdhsa_user_sgpr_dispatch_id 0
		.amdhsa_user_sgpr_kernarg_preload_length 0
		.amdhsa_user_sgpr_kernarg_preload_offset 0
		.amdhsa_user_sgpr_private_segment_size 0
		.amdhsa_uses_dynamic_stack 0
		.amdhsa_enable_private_segment 0
		.amdhsa_system_sgpr_workgroup_id_x 1
		.amdhsa_system_sgpr_workgroup_id_y 0
		.amdhsa_system_sgpr_workgroup_id_z 0
		.amdhsa_system_sgpr_workgroup_info 0
		.amdhsa_system_vgpr_workitem_id 2
		.amdhsa_next_free_vgpr 240
		.amdhsa_next_free_sgpr 101
		.amdhsa_accum_offset 240
		.amdhsa_reserve_vcc 1
		.amdhsa_float_round_mode_32 0
		.amdhsa_float_round_mode_16_64 0
		.amdhsa_float_denorm_mode_32 3
		.amdhsa_float_denorm_mode_16_64 3
		.amdhsa_dx10_clamp 1
		.amdhsa_ieee_mode 1
		.amdhsa_fp16_overflow 0
		.amdhsa_tg_split 0
		.amdhsa_exception_fp_ieee_invalid_op 0
		.amdhsa_exception_fp_denorm_src 0
		.amdhsa_exception_fp_ieee_div_zero 0
		.amdhsa_exception_fp_ieee_overflow 0
		.amdhsa_exception_fp_ieee_underflow 0
		.amdhsa_exception_fp_ieee_inexact 0
		.amdhsa_exception_int_div_zero 0
	.end_amdhsa_kernel

; __global__ void __launch_bounds__(512) mega(Params p, int ph_lo, int ph_hi) {
;   __shared__ __align__(16) unsigned char smem[SMEM_BYTES];
amdhsa.kernels:
  - .agpr_count:     0
    .args:
      - .offset:         0
        .size:           184
        .value_kind:     by_value
      - .offset:         184
        .size:           4
        .value_kind:     by_value
      - .offset:         188
        .size:           4
        .value_kind:     by_value
      - .offset:         192
        .size:           4
        .value_kind:     hidden_block_count_x
      - .offset:         196
        .size:           4
        .value_kind:     hidden_block_count_y
      - .offset:         200
        .size:           4
        .value_kind:     hidden_block_count_z
      - .offset:         204
        .size:           2
        .value_kind:     hidden_group_size_x
      - .offset:         206
        .size:           2
        .value_kind:     hidden_group_size_y
      - .offset:         208
        .size:           2
        .value_kind:     hidden_group_size_z
      - .offset:         210
        .size:           2
        .value_kind:     hidden_remainder_x
      - .offset:         212
        .size:           2
        .value_kind:     hidden_remainder_y
      - .offset:         214
        .size:           2
        .value_kind:     hidden_remainder_z
      - .offset:         232
        .size:           8
        .value_kind:     hidden_global_offset_x
      - .offset:         240
        .size:           8
        .value_kind:     hidden_global_offset_y
      - .offset:         248
        .size:           8
        .value_kind:     hidden_global_offset_z
      - .offset:         256
        .size:           2
        .value_kind:     hidden_grid_dims
      - .offset:         280
        .size:           8
        .value_kind:     hidden_multigrid_sync_arg
    .group_segment_fixed_size: 139264
    .kernarg_segment_align: 8
    .kernarg_segment_size: 448
    .language:       OpenCL C
    .language_version:
      - 2
      - 0
    .max_flat_workgroup_size: 512
    .name:           _Z4mega6Paramsii
    .private_segment_fixed_size: 0
    .sgpr_count:     107
    .sgpr_spill_count: 92
    .symbol:         _Z4mega6Paramsii.kd
    .uniform_work_group_size: 1
    .uses_dynamic_stack: false
    .vgpr_count:     240
    .vgpr_spill_count: 0
    .wavefront_size: 64
